# rw_task<2> step loop: (sa0,sa1)/(x0,x1)/(t0,t1)/(o0,o1) as register pairs with packed ops, one ds_write2_b32 per step (-4 instr/step)
# speedup vs baseline: 1.0108x; 1.0035x over previous
; #define LAS __attribute__((address_space(3)))
; template <int R>
; __device__ __forceinline__ void rw_task(const Params& p, LAS unsigned char* shm, const int tid, const int s, const int d, const int h, const int half) {
;     ...
;                     const float v0 = sb[320 + row0], v1 = R == 2 ? sb[320 + row1] : 0.f; const f32x2 sc = *(const LAS f32x2*)(sb + 384); const float br = sc[0], kr = sc[1];
;                     if constexpr (R == 2) {
;                     f32x2 pa0 = s0[0] * kk[0], px0 = s0[0] * wr[0], pa1 = s1[0] * kk[0], px1 = s1[0] * wr[0];
; #pragma unroll
;                     for (int e = 1; e < 4; ++e) { pa0 += s0[e] * kk[e]; px0 += s0[e] * wr[e]; pa1 += s1[e] * kk[e]; px1 += s1[e] * wr[e]; }
;                     const float sa0 = red8(pa0[0] + pa0[1]), x0 = red8(px0[0] + px0[1]), sa1 = red8(pa1[0] + pa1[1]), x1 = red8(px1[0] + px1[1]);
;                     const float o0 = x0 - sa0 * br + v0 * kr, o1 = x1 - sa1 * br + v1 * kr;
;                     const f32x2 nsa0 = (f32x2){-sa0, -sa0}, nsa1 = (f32x2){-sa1, -sa1}, vv0 = (f32x2){v0, v0}, vv1 = (f32x2){v1, v1};
; #pragma unroll
;                     for (int e = 0; e < 4; ++e) { s0[e] = s0[e] * ww[e] + nsa0 * bb[e] + vv0 * kc[e]; s1[e] = s1[e] * ww[e] + nsa1 * bb[e] + vv1 * kc[e]; }
;                     ow0[(st * 64) & omask] = o0; ow1[(st * 64) & omask] = o1;
.Lrw2_step:
	ds_read_b128 v[74:77], v130 offset:1552
	ds_read_b128 v[78:81], v130 offset:1568
	ds_read_b128 v[82:85], v130 offset:1808
	ds_read_b128 v[86:89], v130 offset:1824
	ds_read_b128 v[92:95], v130 offset:2064
	ds_read_b128 v[96:99], v130 offset:2080
	ds_read_b128 v[100:103], v130 offset:2320
	ds_read_b128 v[104:107], v130 offset:2336
	ds_read_b128 v[108:111], v130 offset:2576
	ds_read_b128 v[112:115], v130 offset:2592
	ds_read_b32 v116, v132 offset:1552
	ds_read_b32 v117, v132 offset:1584
	ds_read_b64 v[118:119], v133 offset:3088
	s_waitcnt lgkmcnt(13)
	v_pk_mul_f32 v[120:121], v[10:11], v[36:37]
	v_pk_mul_f32 v[124:125], v[2:3], v[36:37]
	v_pk_mul_f32 v[122:123], v[10:11], v[60:61]
	v_pk_mul_f32 v[126:127], v[2:3], v[60:61]
	v_pk_fma_f32 v[120:121], v[12:13], v[38:39], v[120:121]
	v_pk_fma_f32 v[124:125], v[4:5], v[38:39], v[124:125]
	v_pk_fma_f32 v[122:123], v[12:13], v[62:63], v[122:123]
	v_pk_fma_f32 v[126:127], v[4:5], v[62:63], v[126:127]
	v_pk_fma_f32 v[120:121], v[14:15], v[40:41], v[120:121]
	v_pk_fma_f32 v[124:125], v[6:7], v[40:41], v[124:125]
	v_pk_fma_f32 v[122:123], v[14:15], v[64:65], v[122:123]
	v_pk_fma_f32 v[126:127], v[6:7], v[64:65], v[126:127]
	v_pk_fma_f32 v[120:121], v[16:17], v[42:43], v[120:121]
	v_pk_fma_f32 v[124:125], v[8:9], v[42:43], v[124:125]
	v_pk_fma_f32 v[122:123], v[16:17], v[66:67], v[122:123]
	v_pk_fma_f32 v[126:127], v[8:9], v[66:67], v[126:127]
	v_pk_mul_f32 v[136:137], v[10:11], v[28:29]
	v_pk_mul_f32 v[148:149], v[2:3], v[28:29]
	v_add_f32_e32 v160, v120, v121
	v_add_f32_e32 v161, v124, v125
	v_add_f32_e32 v162, v122, v123
	v_add_f32_e32 v163, v126, v127
	v_pk_mul_f32 v[138:139], v[12:13], v[30:31]
	v_pk_mul_f32 v[150:151], v[4:5], v[30:31]
	v_add_f32_dpp v160, v160, v160 quad_perm:[1,0,3,2] row_mask:0xf bank_mask:0xf bound_ctrl:1
	v_add_f32_dpp v161, v161, v161 quad_perm:[1,0,3,2] row_mask:0xf bank_mask:0xf bound_ctrl:1
	v_pk_mul_f32 v[140:141], v[14:15], v[32:33]
	v_pk_mul_f32 v[152:153], v[6:7], v[32:33]
	v_add_f32_dpp v162, v162, v162 quad_perm:[1,0,3,2] row_mask:0xf bank_mask:0xf bound_ctrl:1
	v_add_f32_dpp v163, v163, v163 quad_perm:[1,0,3,2] row_mask:0xf bank_mask:0xf bound_ctrl:1
	v_pk_mul_f32 v[142:143], v[16:17], v[34:35]
	v_pk_mul_f32 v[154:155], v[8:9], v[34:35]
	v_add_f32_dpp v160, v160, v160 quad_perm:[2,3,0,1] row_mask:0xf bank_mask:0xf bound_ctrl:1
	v_add_f32_dpp v161, v161, v161 quad_perm:[2,3,0,1] row_mask:0xf bank_mask:0xf bound_ctrl:1
	v_pk_fma_f32 v[136:137], v[52:53], v[68:69], v[136:137] op_sel_hi:[1,0,1]
	v_pk_fma_f32 v[148:149], v[52:53], v[68:69], v[148:149] op_sel:[0,1,0] op_sel_hi:[1,1,1]
	v_add_f32_dpp v162, v162, v162 quad_perm:[2,3,0,1] row_mask:0xf bank_mask:0xf bound_ctrl:1
	v_add_f32_dpp v163, v163, v163 quad_perm:[2,3,0,1] row_mask:0xf bank_mask:0xf bound_ctrl:1
	v_pk_fma_f32 v[138:139], v[54:55], v[68:69], v[138:139] op_sel_hi:[1,0,1]
	v_pk_fma_f32 v[150:151], v[54:55], v[68:69], v[150:151] op_sel:[0,1,0] op_sel_hi:[1,1,1]
	v_add_f32_dpp v160, v160, v160 row_half_mirror row_mask:0xf bank_mask:0xf bound_ctrl:1
	v_add_f32_dpp v161, v161, v161 row_half_mirror row_mask:0xf bank_mask:0xf bound_ctrl:1
	v_pk_fma_f32 v[140:141], v[56:57], v[68:69], v[140:141] op_sel_hi:[1,0,1]
	v_pk_fma_f32 v[152:153], v[56:57], v[68:69], v[152:153] op_sel:[0,1,0] op_sel_hi:[1,1,1]
	v_add_f32_dpp v162, v162, v162 row_half_mirror row_mask:0xf bank_mask:0xf bound_ctrl:1
	v_add_f32_dpp v163, v163, v163 row_half_mirror row_mask:0xf bank_mask:0xf bound_ctrl:1
	v_pk_fma_f32 v[142:143], v[58:59], v[68:69], v[142:143] op_sel_hi:[1,0,1]
	v_pk_fma_f32 v[154:155], v[58:59], v[68:69], v[154:155] op_sel:[0,1,0] op_sel_hi:[1,1,1]
	v_pk_mul_f32 v[144:145], v[68:69], v[70:71] op_sel:[0,1] op_sel_hi:[1,1]
	v_pk_fma_f32 v[10:11], v[44:45], v[160:161], v[136:137] op_sel_hi:[1,0,1] neg_lo:[0,1,0] neg_hi:[0,1,0]
	v_pk_fma_f32 v[2:3], v[44:45], v[160:161], v[148:149] op_sel:[0,1,0] op_sel_hi:[1,1,1] neg_lo:[0,1,0] neg_hi:[0,1,0]
	v_pk_fma_f32 v[144:145], v[160:161], v[70:71], v[144:145] op_sel_hi:[1,0,1] neg_lo:[1,0,0] neg_hi:[1,0,0]
	v_pk_fma_f32 v[12:13], v[46:47], v[160:161], v[138:139] op_sel_hi:[1,0,1] neg_lo:[0,1,0] neg_hi:[0,1,0]
	v_pk_fma_f32 v[4:5], v[46:47], v[160:161], v[150:151] op_sel:[0,1,0] op_sel_hi:[1,1,1] neg_lo:[0,1,0] neg_hi:[0,1,0]
	v_pk_add_f32 v[128:129], v[162:163], v[144:145]
	v_pk_fma_f32 v[14:15], v[48:49], v[160:161], v[140:141] op_sel_hi:[1,0,1] neg_lo:[0,1,0] neg_hi:[0,1,0]
	v_pk_fma_f32 v[6:7], v[48:49], v[160:161], v[152:153] op_sel:[0,1,0] op_sel_hi:[1,1,1] neg_lo:[0,1,0] neg_hi:[0,1,0]
	v_pk_fma_f32 v[16:17], v[50:51], v[160:161], v[142:143] op_sel_hi:[1,0,1] neg_lo:[0,1,0] neg_hi:[0,1,0]
	v_pk_fma_f32 v[8:9], v[50:51], v[160:161], v[154:155] op_sel:[0,1,0] op_sel_hi:[1,1,1] neg_lo:[0,1,0] neg_hi:[0,1,0]
	ds_write2_b32 v156, v128, v129 offset0:0 offset1:8
	ds_read_b128 v[28:31], v130 offset:3104
	ds_read_b128 v[32:35], v130 offset:3120
	ds_read_b128 v[36:39], v130 offset:3360
	ds_read_b128 v[40:43], v130 offset:3376
	ds_read_b128 v[44:47], v130 offset:3616
	ds_read_b128 v[48:51], v130 offset:3632
	ds_read_b128 v[52:55], v130 offset:3872
	ds_read_b128 v[56:59], v130 offset:3888
	ds_read_b128 v[60:63], v130 offset:4128
	ds_read_b128 v[64:67], v130 offset:4144
	ds_read_b32 v68, v132 offset:3104
	ds_read_b32 v69, v132 offset:3136
	ds_read_b64 v[70:71], v133 offset:4640
	s_waitcnt lgkmcnt(13)
; #define LAS __attribute__((address_space(3)))
; template <int R>
; __device__ __forceinline__ void rw_task(const Params& p, LAS unsigned char* shm, const int tid, const int s, const int d, const int h, const int half) {
;     ...
;                     const float v0 = sb[320 + row0], v1 = R == 2 ? sb[320 + row1] : 0.f; const f32x2 sc = *(const LAS f32x2*)(sb + 384); const float br = sc[0], kr = sc[1];
;                     if constexpr (R == 2) {
;                     f32x2 pa0 = s0[0] * kk[0], px0 = s0[0] * wr[0], pa1 = s1[0] * kk[0], px1 = s1[0] * wr[0];
; #pragma unroll
;                     for (int e = 1; e < 4; ++e) { pa0 += s0[e] * kk[e]; px0 += s0[e] * wr[e]; pa1 += s1[e] * kk[e]; px1 += s1[e] * wr[e]; }
;                     const float sa0 = red8(pa0[0] + pa0[1]), x0 = red8(px0[0] + px0[1]), sa1 = red8(pa1[0] + pa1[1]), x1 = red8(px1[0] + px1[1]);
;                     const float o0 = x0 - sa0 * br + v0 * kr, o1 = x1 - sa1 * br + v1 * kr;
;                     const f32x2 nsa0 = (f32x2){-sa0, -sa0}, nsa1 = (f32x2){-sa1, -sa1}, vv0 = (f32x2){v0, v0}, vv1 = (f32x2){v1, v1};
; #pragma unroll
;                     for (int e = 0; e < 4; ++e) { s0[e] = s0[e] * ww[e] + nsa0 * bb[e] + vv0 * kc[e]; s1[e] = s1[e] * ww[e] + nsa1 * bb[e] + vv1 * kc[e]; }
;                     ow0[(st * 64) & omask] = o0; ow1[(st * 64) & omask] = o1;
	v_pk_mul_f32 v[120:121], v[10:11], v[82:83]
	v_pk_mul_f32 v[124:125], v[2:3], v[82:83]
	v_pk_mul_f32 v[122:123], v[10:11], v[108:109]
	v_pk_mul_f32 v[126:127], v[2:3], v[108:109]
	v_pk_fma_f32 v[120:121], v[12:13], v[84:85], v[120:121]
	v_pk_fma_f32 v[124:125], v[4:5], v[84:85], v[124:125]
	v_pk_fma_f32 v[122:123], v[12:13], v[110:111], v[122:123]
	v_pk_fma_f32 v[126:127], v[4:5], v[110:111], v[126:127]
	v_pk_fma_f32 v[120:121], v[14:15], v[86:87], v[120:121]
	v_pk_fma_f32 v[124:125], v[6:7], v[86:87], v[124:125]
	v_pk_fma_f32 v[122:123], v[14:15], v[112:113], v[122:123]
	v_pk_fma_f32 v[126:127], v[6:7], v[112:113], v[126:127]
	v_pk_fma_f32 v[120:121], v[16:17], v[88:89], v[120:121]
	v_pk_fma_f32 v[124:125], v[8:9], v[88:89], v[124:125]
	v_pk_fma_f32 v[122:123], v[16:17], v[114:115], v[122:123]
	v_pk_fma_f32 v[126:127], v[8:9], v[114:115], v[126:127]
	v_pk_mul_f32 v[136:137], v[10:11], v[74:75]
	v_pk_mul_f32 v[148:149], v[2:3], v[74:75]
	v_add_f32_e32 v160, v120, v121
	v_add_f32_e32 v161, v124, v125
	v_add_f32_e32 v162, v122, v123
	v_add_f32_e32 v163, v126, v127
	v_pk_mul_f32 v[138:139], v[12:13], v[76:77]
	v_pk_mul_f32 v[150:151], v[4:5], v[76:77]
	v_add_f32_dpp v160, v160, v160 quad_perm:[1,0,3,2] row_mask:0xf bank_mask:0xf bound_ctrl:1
	v_add_f32_dpp v161, v161, v161 quad_perm:[1,0,3,2] row_mask:0xf bank_mask:0xf bound_ctrl:1
	v_pk_mul_f32 v[140:141], v[14:15], v[78:79]
	v_pk_mul_f32 v[152:153], v[6:7], v[78:79]
	v_add_f32_dpp v162, v162, v162 quad_perm:[1,0,3,2] row_mask:0xf bank_mask:0xf bound_ctrl:1
	v_add_f32_dpp v163, v163, v163 quad_perm:[1,0,3,2] row_mask:0xf bank_mask:0xf bound_ctrl:1
	v_pk_mul_f32 v[142:143], v[16:17], v[80:81]
	v_pk_mul_f32 v[154:155], v[8:9], v[80:81]
	v_add_f32_dpp v160, v160, v160 quad_perm:[2,3,0,1] row_mask:0xf bank_mask:0xf bound_ctrl:1
	v_add_f32_dpp v161, v161, v161 quad_perm:[2,3,0,1] row_mask:0xf bank_mask:0xf bound_ctrl:1
	v_pk_fma_f32 v[136:137], v[100:101], v[116:117], v[136:137] op_sel_hi:[1,0,1]
	v_pk_fma_f32 v[148:149], v[100:101], v[116:117], v[148:149] op_sel:[0,1,0] op_sel_hi:[1,1,1]
	v_add_f32_dpp v162, v162, v162 quad_perm:[2,3,0,1] row_mask:0xf bank_mask:0xf bound_ctrl:1
	v_add_f32_dpp v163, v163, v163 quad_perm:[2,3,0,1] row_mask:0xf bank_mask:0xf bound_ctrl:1
	v_pk_fma_f32 v[138:139], v[102:103], v[116:117], v[138:139] op_sel_hi:[1,0,1]
	v_pk_fma_f32 v[150:151], v[102:103], v[116:117], v[150:151] op_sel:[0,1,0] op_sel_hi:[1,1,1]
	v_add_f32_dpp v160, v160, v160 row_half_mirror row_mask:0xf bank_mask:0xf bound_ctrl:1
	v_add_f32_dpp v161, v161, v161 row_half_mirror row_mask:0xf bank_mask:0xf bound_ctrl:1
	v_pk_fma_f32 v[140:141], v[104:105], v[116:117], v[140:141] op_sel_hi:[1,0,1]
	v_pk_fma_f32 v[152:153], v[104:105], v[116:117], v[152:153] op_sel:[0,1,0] op_sel_hi:[1,1,1]
	v_add_f32_dpp v162, v162, v162 row_half_mirror row_mask:0xf bank_mask:0xf bound_ctrl:1
	v_add_f32_dpp v163, v163, v163 row_half_mirror row_mask:0xf bank_mask:0xf bound_ctrl:1
	v_pk_fma_f32 v[142:143], v[106:107], v[116:117], v[142:143] op_sel_hi:[1,0,1]
	v_pk_fma_f32 v[154:155], v[106:107], v[116:117], v[154:155] op_sel:[0,1,0] op_sel_hi:[1,1,1]
	v_pk_mul_f32 v[144:145], v[116:117], v[118:119] op_sel:[0,1] op_sel_hi:[1,1]
	v_pk_fma_f32 v[10:11], v[92:93], v[160:161], v[136:137] op_sel_hi:[1,0,1] neg_lo:[0,1,0] neg_hi:[0,1,0]
	v_pk_fma_f32 v[2:3], v[92:93], v[160:161], v[148:149] op_sel:[0,1,0] op_sel_hi:[1,1,1] neg_lo:[0,1,0] neg_hi:[0,1,0]
	v_pk_fma_f32 v[144:145], v[160:161], v[118:119], v[144:145] op_sel_hi:[1,0,1] neg_lo:[1,0,0] neg_hi:[1,0,0]
	v_pk_fma_f32 v[12:13], v[94:95], v[160:161], v[138:139] op_sel_hi:[1,0,1] neg_lo:[0,1,0] neg_hi:[0,1,0]
	v_pk_fma_f32 v[4:5], v[94:95], v[160:161], v[150:151] op_sel:[0,1,0] op_sel_hi:[1,1,1] neg_lo:[0,1,0] neg_hi:[0,1,0]
	v_pk_add_f32 v[128:129], v[162:163], v[144:145]
	v_pk_fma_f32 v[14:15], v[96:97], v[160:161], v[140:141] op_sel_hi:[1,0,1] neg_lo:[0,1,0] neg_hi:[0,1,0]
	v_pk_fma_f32 v[6:7], v[96:97], v[160:161], v[152:153] op_sel:[0,1,0] op_sel_hi:[1,1,1] neg_lo:[0,1,0] neg_hi:[0,1,0]
	v_pk_fma_f32 v[16:17], v[98:99], v[160:161], v[142:143] op_sel_hi:[1,0,1] neg_lo:[0,1,0] neg_hi:[0,1,0]
	v_pk_fma_f32 v[8:9], v[98:99], v[160:161], v[154:155] op_sel:[0,1,0] op_sel_hi:[1,1,1] neg_lo:[0,1,0] neg_hi:[0,1,0]
	ds_write2_b32 v156, v128, v129 offset0:64 offset1:72
	ds_read_b128 v[74:77], v130 offset:4656
	ds_read_b128 v[78:81], v130 offset:4672
	ds_read_b128 v[82:85], v130 offset:4912
	ds_read_b128 v[86:89], v130 offset:4928
	ds_read_b128 v[92:95], v130 offset:5168
	ds_read_b128 v[96:99], v130 offset:5184
	ds_read_b128 v[100:103], v130 offset:5424
	ds_read_b128 v[104:107], v130 offset:5440
	ds_read_b128 v[108:111], v130 offset:5680
	ds_read_b128 v[112:115], v130 offset:5696
	ds_read_b32 v116, v132 offset:4656
	ds_read_b32 v117, v132 offset:4688
	ds_read_b64 v[118:119], v133 offset:6192
	s_waitcnt lgkmcnt(13)
; #define LAS __attribute__((address_space(3)))
; template <int R>
; __device__ __forceinline__ void rw_task(const Params& p, LAS unsigned char* shm, const int tid, const int s, const int d, const int h, const int half) {
;     ...
;                     const float v0 = sb[320 + row0], v1 = R == 2 ? sb[320 + row1] : 0.f; const f32x2 sc = *(const LAS f32x2*)(sb + 384); const float br = sc[0], kr = sc[1];
;                     if constexpr (R == 2) {
;                     f32x2 pa0 = s0[0] * kk[0], px0 = s0[0] * wr[0], pa1 = s1[0] * kk[0], px1 = s1[0] * wr[0];
; #pragma unroll
;                     for (int e = 1; e < 4; ++e) { pa0 += s0[e] * kk[e]; px0 += s0[e] * wr[e]; pa1 += s1[e] * kk[e]; px1 += s1[e] * wr[e]; }
;                     const float sa0 = red8(pa0[0] + pa0[1]), x0 = red8(px0[0] + px0[1]), sa1 = red8(pa1[0] + pa1[1]), x1 = red8(px1[0] + px1[1]);
;                     const float o0 = x0 - sa0 * br + v0 * kr, o1 = x1 - sa1 * br + v1 * kr;
;                     const f32x2 nsa0 = (f32x2){-sa0, -sa0}, nsa1 = (f32x2){-sa1, -sa1}, vv0 = (f32x2){v0, v0}, vv1 = (f32x2){v1, v1};
; #pragma unroll
;                     for (int e = 0; e < 4; ++e) { s0[e] = s0[e] * ww[e] + nsa0 * bb[e] + vv0 * kc[e]; s1[e] = s1[e] * ww[e] + nsa1 * bb[e] + vv1 * kc[e]; }
;                     ow0[(st * 64) & omask] = o0; ow1[(st * 64) & omask] = o1;
	v_pk_mul_f32 v[120:121], v[10:11], v[36:37]
	v_pk_mul_f32 v[124:125], v[2:3], v[36:37]
	v_pk_mul_f32 v[122:123], v[10:11], v[60:61]
	v_pk_mul_f32 v[126:127], v[2:3], v[60:61]
	v_pk_fma_f32 v[120:121], v[12:13], v[38:39], v[120:121]
	v_pk_fma_f32 v[124:125], v[4:5], v[38:39], v[124:125]
	v_pk_fma_f32 v[122:123], v[12:13], v[62:63], v[122:123]
	v_pk_fma_f32 v[126:127], v[4:5], v[62:63], v[126:127]
	v_pk_fma_f32 v[120:121], v[14:15], v[40:41], v[120:121]
	v_pk_fma_f32 v[124:125], v[6:7], v[40:41], v[124:125]
	v_pk_fma_f32 v[122:123], v[14:15], v[64:65], v[122:123]
	v_pk_fma_f32 v[126:127], v[6:7], v[64:65], v[126:127]
	v_pk_fma_f32 v[120:121], v[16:17], v[42:43], v[120:121]
	v_pk_fma_f32 v[124:125], v[8:9], v[42:43], v[124:125]
	v_pk_fma_f32 v[122:123], v[16:17], v[66:67], v[122:123]
	v_pk_fma_f32 v[126:127], v[8:9], v[66:67], v[126:127]
	v_pk_mul_f32 v[136:137], v[10:11], v[28:29]
	v_pk_mul_f32 v[148:149], v[2:3], v[28:29]
	v_add_f32_e32 v160, v120, v121
	v_add_f32_e32 v161, v124, v125
	v_add_f32_e32 v162, v122, v123
	v_add_f32_e32 v163, v126, v127
	v_pk_mul_f32 v[138:139], v[12:13], v[30:31]
	v_pk_mul_f32 v[150:151], v[4:5], v[30:31]
	v_add_f32_dpp v160, v160, v160 quad_perm:[1,0,3,2] row_mask:0xf bank_mask:0xf bound_ctrl:1
	v_add_f32_dpp v161, v161, v161 quad_perm:[1,0,3,2] row_mask:0xf bank_mask:0xf bound_ctrl:1
	v_pk_mul_f32 v[140:141], v[14:15], v[32:33]
	v_pk_mul_f32 v[152:153], v[6:7], v[32:33]
	v_add_f32_dpp v162, v162, v162 quad_perm:[1,0,3,2] row_mask:0xf bank_mask:0xf bound_ctrl:1
	v_add_f32_dpp v163, v163, v163 quad_perm:[1,0,3,2] row_mask:0xf bank_mask:0xf bound_ctrl:1
	v_pk_mul_f32 v[142:143], v[16:17], v[34:35]
	v_pk_mul_f32 v[154:155], v[8:9], v[34:35]
	v_add_f32_dpp v160, v160, v160 quad_perm:[2,3,0,1] row_mask:0xf bank_mask:0xf bound_ctrl:1
	v_add_f32_dpp v161, v161, v161 quad_perm:[2,3,0,1] row_mask:0xf bank_mask:0xf bound_ctrl:1
	v_pk_fma_f32 v[136:137], v[52:53], v[68:69], v[136:137] op_sel_hi:[1,0,1]
	v_pk_fma_f32 v[148:149], v[52:53], v[68:69], v[148:149] op_sel:[0,1,0] op_sel_hi:[1,1,1]
	v_add_f32_dpp v162, v162, v162 quad_perm:[2,3,0,1] row_mask:0xf bank_mask:0xf bound_ctrl:1
	v_add_f32_dpp v163, v163, v163 quad_perm:[2,3,0,1] row_mask:0xf bank_mask:0xf bound_ctrl:1
	v_pk_fma_f32 v[138:139], v[54:55], v[68:69], v[138:139] op_sel_hi:[1,0,1]
	v_pk_fma_f32 v[150:151], v[54:55], v[68:69], v[150:151] op_sel:[0,1,0] op_sel_hi:[1,1,1]
	v_add_f32_dpp v160, v160, v160 row_half_mirror row_mask:0xf bank_mask:0xf bound_ctrl:1
	v_add_f32_dpp v161, v161, v161 row_half_mirror row_mask:0xf bank_mask:0xf bound_ctrl:1
	v_pk_fma_f32 v[140:141], v[56:57], v[68:69], v[140:141] op_sel_hi:[1,0,1]
	v_pk_fma_f32 v[152:153], v[56:57], v[68:69], v[152:153] op_sel:[0,1,0] op_sel_hi:[1,1,1]
	v_add_f32_dpp v162, v162, v162 row_half_mirror row_mask:0xf bank_mask:0xf bound_ctrl:1
	v_add_f32_dpp v163, v163, v163 row_half_mirror row_mask:0xf bank_mask:0xf bound_ctrl:1
	v_pk_fma_f32 v[142:143], v[58:59], v[68:69], v[142:143] op_sel_hi:[1,0,1]
	v_pk_fma_f32 v[154:155], v[58:59], v[68:69], v[154:155] op_sel:[0,1,0] op_sel_hi:[1,1,1]
	v_pk_mul_f32 v[144:145], v[68:69], v[70:71] op_sel:[0,1] op_sel_hi:[1,1]
	v_pk_fma_f32 v[10:11], v[44:45], v[160:161], v[136:137] op_sel_hi:[1,0,1] neg_lo:[0,1,0] neg_hi:[0,1,0]
	v_pk_fma_f32 v[2:3], v[44:45], v[160:161], v[148:149] op_sel:[0,1,0] op_sel_hi:[1,1,1] neg_lo:[0,1,0] neg_hi:[0,1,0]
	v_pk_fma_f32 v[144:145], v[160:161], v[70:71], v[144:145] op_sel_hi:[1,0,1] neg_lo:[1,0,0] neg_hi:[1,0,0]
	v_pk_fma_f32 v[12:13], v[46:47], v[160:161], v[138:139] op_sel_hi:[1,0,1] neg_lo:[0,1,0] neg_hi:[0,1,0]
	v_pk_fma_f32 v[4:5], v[46:47], v[160:161], v[150:151] op_sel:[0,1,0] op_sel_hi:[1,1,1] neg_lo:[0,1,0] neg_hi:[0,1,0]
	v_pk_add_f32 v[128:129], v[162:163], v[144:145]
	v_pk_fma_f32 v[14:15], v[48:49], v[160:161], v[140:141] op_sel_hi:[1,0,1] neg_lo:[0,1,0] neg_hi:[0,1,0]
	v_pk_fma_f32 v[6:7], v[48:49], v[160:161], v[152:153] op_sel:[0,1,0] op_sel_hi:[1,1,1] neg_lo:[0,1,0] neg_hi:[0,1,0]
	v_pk_fma_f32 v[16:17], v[50:51], v[160:161], v[142:143] op_sel_hi:[1,0,1] neg_lo:[0,1,0] neg_hi:[0,1,0]
	v_pk_fma_f32 v[8:9], v[50:51], v[160:161], v[154:155] op_sel:[0,1,0] op_sel_hi:[1,1,1] neg_lo:[0,1,0] neg_hi:[0,1,0]
	ds_write2_b32 v156, v128, v129 offset0:128 offset1:136
	ds_read_b128 v[28:31], v130 offset:6208
	ds_read_b128 v[32:35], v130 offset:6224
	ds_read_b128 v[36:39], v130 offset:6464
	ds_read_b128 v[40:43], v130 offset:6480
	ds_read_b128 v[44:47], v130 offset:6720
	ds_read_b128 v[48:51], v130 offset:6736
	ds_read_b128 v[52:55], v130 offset:6976
	ds_read_b128 v[56:59], v130 offset:6992
	ds_read_b128 v[60:63], v130 offset:7232
	ds_read_b128 v[64:67], v130 offset:7248
	ds_read_b32 v68, v132 offset:6208
	ds_read_b32 v69, v132 offset:6240
	ds_read_b64 v[70:71], v133 offset:7744
	s_waitcnt lgkmcnt(13)
; #define LAS __attribute__((address_space(3)))
; template <int R>
; __device__ __forceinline__ void rw_task(const Params& p, LAS unsigned char* shm, const int tid, const int s, const int d, const int h, const int half) {
;     ...
;                     const float v0 = sb[320 + row0], v1 = R == 2 ? sb[320 + row1] : 0.f; const f32x2 sc = *(const LAS f32x2*)(sb + 384); const float br = sc[0], kr = sc[1];
;                     if constexpr (R == 2) {
;                     f32x2 pa0 = s0[0] * kk[0], px0 = s0[0] * wr[0], pa1 = s1[0] * kk[0], px1 = s1[0] * wr[0];
; #pragma unroll
;                     for (int e = 1; e < 4; ++e) { pa0 += s0[e] * kk[e]; px0 += s0[e] * wr[e]; pa1 += s1[e] * kk[e]; px1 += s1[e] * wr[e]; }
;                     const float sa0 = red8(pa0[0] + pa0[1]), x0 = red8(px0[0] + px0[1]), sa1 = red8(pa1[0] + pa1[1]), x1 = red8(px1[0] + px1[1]);
;                     const float o0 = x0 - sa0 * br + v0 * kr, o1 = x1 - sa1 * br + v1 * kr;
;                     const f32x2 nsa0 = (f32x2){-sa0, -sa0}, nsa1 = (f32x2){-sa1, -sa1}, vv0 = (f32x2){v0, v0}, vv1 = (f32x2){v1, v1};
; #pragma unroll
;                     for (int e = 0; e < 4; ++e) { s0[e] = s0[e] * ww[e] + nsa0 * bb[e] + vv0 * kc[e]; s1[e] = s1[e] * ww[e] + nsa1 * bb[e] + vv1 * kc[e]; }
;                     ow0[(st * 64) & omask] = o0; ow1[(st * 64) & omask] = o1;
	v_pk_mul_f32 v[120:121], v[10:11], v[82:83]
	v_pk_mul_f32 v[124:125], v[2:3], v[82:83]
	v_pk_mul_f32 v[122:123], v[10:11], v[108:109]
	v_pk_mul_f32 v[126:127], v[2:3], v[108:109]
	v_pk_fma_f32 v[120:121], v[12:13], v[84:85], v[120:121]
	v_pk_fma_f32 v[124:125], v[4:5], v[84:85], v[124:125]
	v_pk_fma_f32 v[122:123], v[12:13], v[110:111], v[122:123]
	v_pk_fma_f32 v[126:127], v[4:5], v[110:111], v[126:127]
	v_pk_fma_f32 v[120:121], v[14:15], v[86:87], v[120:121]
	v_pk_fma_f32 v[124:125], v[6:7], v[86:87], v[124:125]
	v_pk_fma_f32 v[122:123], v[14:15], v[112:113], v[122:123]
	v_pk_fma_f32 v[126:127], v[6:7], v[112:113], v[126:127]
	v_pk_fma_f32 v[120:121], v[16:17], v[88:89], v[120:121]
	v_pk_fma_f32 v[124:125], v[8:9], v[88:89], v[124:125]
	v_pk_fma_f32 v[122:123], v[16:17], v[114:115], v[122:123]
	v_pk_fma_f32 v[126:127], v[8:9], v[114:115], v[126:127]
	v_pk_mul_f32 v[136:137], v[10:11], v[74:75]
	v_pk_mul_f32 v[148:149], v[2:3], v[74:75]
	v_add_f32_e32 v160, v120, v121
	v_add_f32_e32 v161, v124, v125
	v_add_f32_e32 v162, v122, v123
	v_add_f32_e32 v163, v126, v127
	v_pk_mul_f32 v[138:139], v[12:13], v[76:77]
	v_pk_mul_f32 v[150:151], v[4:5], v[76:77]
	v_add_f32_dpp v160, v160, v160 quad_perm:[1,0,3,2] row_mask:0xf bank_mask:0xf bound_ctrl:1
	v_add_f32_dpp v161, v161, v161 quad_perm:[1,0,3,2] row_mask:0xf bank_mask:0xf bound_ctrl:1
	v_pk_mul_f32 v[140:141], v[14:15], v[78:79]
	v_pk_mul_f32 v[152:153], v[6:7], v[78:79]
	v_add_f32_dpp v162, v162, v162 quad_perm:[1,0,3,2] row_mask:0xf bank_mask:0xf bound_ctrl:1
	v_add_f32_dpp v163, v163, v163 quad_perm:[1,0,3,2] row_mask:0xf bank_mask:0xf bound_ctrl:1
	v_pk_mul_f32 v[142:143], v[16:17], v[80:81]
	v_pk_mul_f32 v[154:155], v[8:9], v[80:81]
	v_add_f32_dpp v160, v160, v160 quad_perm:[2,3,0,1] row_mask:0xf bank_mask:0xf bound_ctrl:1
	v_add_f32_dpp v161, v161, v161 quad_perm:[2,3,0,1] row_mask:0xf bank_mask:0xf bound_ctrl:1
	v_pk_fma_f32 v[136:137], v[100:101], v[116:117], v[136:137] op_sel_hi:[1,0,1]
	v_pk_fma_f32 v[148:149], v[100:101], v[116:117], v[148:149] op_sel:[0,1,0] op_sel_hi:[1,1,1]
	v_add_f32_dpp v162, v162, v162 quad_perm:[2,3,0,1] row_mask:0xf bank_mask:0xf bound_ctrl:1
	v_add_f32_dpp v163, v163, v163 quad_perm:[2,3,0,1] row_mask:0xf bank_mask:0xf bound_ctrl:1
	v_pk_fma_f32 v[138:139], v[102:103], v[116:117], v[138:139] op_sel_hi:[1,0,1]
	v_pk_fma_f32 v[150:151], v[102:103], v[116:117], v[150:151] op_sel:[0,1,0] op_sel_hi:[1,1,1]
	v_add_f32_dpp v160, v160, v160 row_half_mirror row_mask:0xf bank_mask:0xf bound_ctrl:1
	v_add_f32_dpp v161, v161, v161 row_half_mirror row_mask:0xf bank_mask:0xf bound_ctrl:1
	v_pk_fma_f32 v[140:141], v[104:105], v[116:117], v[140:141] op_sel_hi:[1,0,1]
	v_pk_fma_f32 v[152:153], v[104:105], v[116:117], v[152:153] op_sel:[0,1,0] op_sel_hi:[1,1,1]
	v_add_f32_dpp v162, v162, v162 row_half_mirror row_mask:0xf bank_mask:0xf bound_ctrl:1
	v_add_f32_dpp v163, v163, v163 row_half_mirror row_mask:0xf bank_mask:0xf bound_ctrl:1
	v_pk_fma_f32 v[142:143], v[106:107], v[116:117], v[142:143] op_sel_hi:[1,0,1]
	v_pk_fma_f32 v[154:155], v[106:107], v[116:117], v[154:155] op_sel:[0,1,0] op_sel_hi:[1,1,1]
	v_pk_mul_f32 v[144:145], v[116:117], v[118:119] op_sel:[0,1] op_sel_hi:[1,1]
	v_pk_fma_f32 v[10:11], v[92:93], v[160:161], v[136:137] op_sel_hi:[1,0,1] neg_lo:[0,1,0] neg_hi:[0,1,0]
	v_pk_fma_f32 v[2:3], v[92:93], v[160:161], v[148:149] op_sel:[0,1,0] op_sel_hi:[1,1,1] neg_lo:[0,1,0] neg_hi:[0,1,0]
	v_pk_fma_f32 v[144:145], v[160:161], v[118:119], v[144:145] op_sel_hi:[1,0,1] neg_lo:[1,0,0] neg_hi:[1,0,0]
	v_pk_fma_f32 v[12:13], v[94:95], v[160:161], v[138:139] op_sel_hi:[1,0,1] neg_lo:[0,1,0] neg_hi:[0,1,0]
	v_pk_fma_f32 v[4:5], v[94:95], v[160:161], v[150:151] op_sel:[0,1,0] op_sel_hi:[1,1,1] neg_lo:[0,1,0] neg_hi:[0,1,0]
	v_pk_add_f32 v[128:129], v[162:163], v[144:145]
	v_pk_fma_f32 v[14:15], v[96:97], v[160:161], v[140:141] op_sel_hi:[1,0,1] neg_lo:[0,1,0] neg_hi:[0,1,0]
	v_pk_fma_f32 v[6:7], v[96:97], v[160:161], v[152:153] op_sel:[0,1,0] op_sel_hi:[1,1,1] neg_lo:[0,1,0] neg_hi:[0,1,0]
	v_pk_fma_f32 v[16:17], v[98:99], v[160:161], v[142:143] op_sel_hi:[1,0,1] neg_lo:[0,1,0] neg_hi:[0,1,0]
	v_pk_fma_f32 v[8:9], v[98:99], v[160:161], v[154:155] op_sel:[0,1,0] op_sel_hi:[1,1,1] neg_lo:[0,1,0] neg_hi:[0,1,0]
	ds_write2_b32 v156, v128, v129 offset0:192 offset1:200
	v_add_u32_e32 v156, 0x400, v156
	ds_read_b128 v[74:77], v130 offset:7760
	ds_read_b128 v[78:81], v130 offset:7776
	ds_read_b128 v[82:85], v130 offset:8016
	ds_read_b128 v[86:89], v130 offset:8032
	ds_read_b128 v[92:95], v130 offset:8272
	ds_read_b128 v[96:99], v130 offset:8288
	ds_read_b128 v[100:103], v130 offset:8528
	ds_read_b128 v[104:107], v130 offset:8544
	ds_read_b128 v[108:111], v130 offset:8784
	ds_read_b128 v[112:115], v130 offset:8800
	ds_read_b32 v116, v132 offset:7760
	ds_read_b32 v117, v132 offset:7792
	ds_read_b64 v[118:119], v133 offset:9296
	s_waitcnt lgkmcnt(13)
; #define LAS __attribute__((address_space(3)))
; template <int R>
; __device__ __forceinline__ void rw_task(const Params& p, LAS unsigned char* shm, const int tid, const int s, const int d, const int h, const int half) {
;     ...
;                     const float v0 = sb[320 + row0], v1 = R == 2 ? sb[320 + row1] : 0.f; const f32x2 sc = *(const LAS f32x2*)(sb + 384); const float br = sc[0], kr = sc[1];
;                     if constexpr (R == 2) {
;                     f32x2 pa0 = s0[0] * kk[0], px0 = s0[0] * wr[0], pa1 = s1[0] * kk[0], px1 = s1[0] * wr[0];
; #pragma unroll
;                     for (int e = 1; e < 4; ++e) { pa0 += s0[e] * kk[e]; px0 += s0[e] * wr[e]; pa1 += s1[e] * kk[e]; px1 += s1[e] * wr[e]; }
;                     const float sa0 = red8(pa0[0] + pa0[1]), x0 = red8(px0[0] + px0[1]), sa1 = red8(pa1[0] + pa1[1]), x1 = red8(px1[0] + px1[1]);
;                     const float o0 = x0 - sa0 * br + v0 * kr, o1 = x1 - sa1 * br + v1 * kr;
;                     const f32x2 nsa0 = (f32x2){-sa0, -sa0}, nsa1 = (f32x2){-sa1, -sa1}, vv0 = (f32x2){v0, v0}, vv1 = (f32x2){v1, v1};
; #pragma unroll
;                     for (int e = 0; e < 4; ++e) { s0[e] = s0[e] * ww[e] + nsa0 * bb[e] + vv0 * kc[e]; s1[e] = s1[e] * ww[e] + nsa1 * bb[e] + vv1 * kc[e]; }
;                     ow0[(st * 64) & omask] = o0; ow1[(st * 64) & omask] = o1;
	v_pk_mul_f32 v[120:121], v[10:11], v[36:37]
	v_pk_mul_f32 v[124:125], v[2:3], v[36:37]
	v_pk_mul_f32 v[122:123], v[10:11], v[60:61]
	v_pk_mul_f32 v[126:127], v[2:3], v[60:61]
	v_pk_fma_f32 v[120:121], v[12:13], v[38:39], v[120:121]
	v_pk_fma_f32 v[124:125], v[4:5], v[38:39], v[124:125]
	v_pk_fma_f32 v[122:123], v[12:13], v[62:63], v[122:123]
	v_pk_fma_f32 v[126:127], v[4:5], v[62:63], v[126:127]
	v_pk_fma_f32 v[120:121], v[14:15], v[40:41], v[120:121]
	v_pk_fma_f32 v[124:125], v[6:7], v[40:41], v[124:125]
	v_pk_fma_f32 v[122:123], v[14:15], v[64:65], v[122:123]
	v_pk_fma_f32 v[126:127], v[6:7], v[64:65], v[126:127]
	v_pk_fma_f32 v[120:121], v[16:17], v[42:43], v[120:121]
	v_pk_fma_f32 v[124:125], v[8:9], v[42:43], v[124:125]
	v_pk_fma_f32 v[122:123], v[16:17], v[66:67], v[122:123]
	v_pk_fma_f32 v[126:127], v[8:9], v[66:67], v[126:127]
	v_pk_mul_f32 v[136:137], v[10:11], v[28:29]
	v_pk_mul_f32 v[148:149], v[2:3], v[28:29]
	v_add_f32_e32 v160, v120, v121
	v_add_f32_e32 v161, v124, v125
	v_add_f32_e32 v162, v122, v123
	v_add_f32_e32 v163, v126, v127
	v_pk_mul_f32 v[138:139], v[12:13], v[30:31]
	v_pk_mul_f32 v[150:151], v[4:5], v[30:31]
	v_add_f32_dpp v160, v160, v160 quad_perm:[1,0,3,2] row_mask:0xf bank_mask:0xf bound_ctrl:1
	v_add_f32_dpp v161, v161, v161 quad_perm:[1,0,3,2] row_mask:0xf bank_mask:0xf bound_ctrl:1
	v_pk_mul_f32 v[140:141], v[14:15], v[32:33]
	v_pk_mul_f32 v[152:153], v[6:7], v[32:33]
	v_add_f32_dpp v162, v162, v162 quad_perm:[1,0,3,2] row_mask:0xf bank_mask:0xf bound_ctrl:1
	v_add_f32_dpp v163, v163, v163 quad_perm:[1,0,3,2] row_mask:0xf bank_mask:0xf bound_ctrl:1
	v_pk_mul_f32 v[142:143], v[16:17], v[34:35]
	v_pk_mul_f32 v[154:155], v[8:9], v[34:35]
	v_add_f32_dpp v160, v160, v160 quad_perm:[2,3,0,1] row_mask:0xf bank_mask:0xf bound_ctrl:1
	v_add_f32_dpp v161, v161, v161 quad_perm:[2,3,0,1] row_mask:0xf bank_mask:0xf bound_ctrl:1
	v_pk_fma_f32 v[136:137], v[52:53], v[68:69], v[136:137] op_sel_hi:[1,0,1]
	v_pk_fma_f32 v[148:149], v[52:53], v[68:69], v[148:149] op_sel:[0,1,0] op_sel_hi:[1,1,1]
	v_add_f32_dpp v162, v162, v162 quad_perm:[2,3,0,1] row_mask:0xf bank_mask:0xf bound_ctrl:1
	v_add_f32_dpp v163, v163, v163 quad_perm:[2,3,0,1] row_mask:0xf bank_mask:0xf bound_ctrl:1
	v_pk_fma_f32 v[138:139], v[54:55], v[68:69], v[138:139] op_sel_hi:[1,0,1]
	v_pk_fma_f32 v[150:151], v[54:55], v[68:69], v[150:151] op_sel:[0,1,0] op_sel_hi:[1,1,1]
	v_add_f32_dpp v160, v160, v160 row_half_mirror row_mask:0xf bank_mask:0xf bound_ctrl:1
	v_add_f32_dpp v161, v161, v161 row_half_mirror row_mask:0xf bank_mask:0xf bound_ctrl:1
	v_pk_fma_f32 v[140:141], v[56:57], v[68:69], v[140:141] op_sel_hi:[1,0,1]
	v_pk_fma_f32 v[152:153], v[56:57], v[68:69], v[152:153] op_sel:[0,1,0] op_sel_hi:[1,1,1]
	v_add_f32_dpp v162, v162, v162 row_half_mirror row_mask:0xf bank_mask:0xf bound_ctrl:1
	v_add_f32_dpp v163, v163, v163 row_half_mirror row_mask:0xf bank_mask:0xf bound_ctrl:1
	v_pk_fma_f32 v[142:143], v[58:59], v[68:69], v[142:143] op_sel_hi:[1,0,1]
	v_pk_fma_f32 v[154:155], v[58:59], v[68:69], v[154:155] op_sel:[0,1,0] op_sel_hi:[1,1,1]
	v_pk_mul_f32 v[144:145], v[68:69], v[70:71] op_sel:[0,1] op_sel_hi:[1,1]
	v_pk_fma_f32 v[10:11], v[44:45], v[160:161], v[136:137] op_sel_hi:[1,0,1] neg_lo:[0,1,0] neg_hi:[0,1,0]
	v_pk_fma_f32 v[2:3], v[44:45], v[160:161], v[148:149] op_sel:[0,1,0] op_sel_hi:[1,1,1] neg_lo:[0,1,0] neg_hi:[0,1,0]
	v_pk_fma_f32 v[144:145], v[160:161], v[70:71], v[144:145] op_sel_hi:[1,0,1] neg_lo:[1,0,0] neg_hi:[1,0,0]
	v_pk_fma_f32 v[12:13], v[46:47], v[160:161], v[138:139] op_sel_hi:[1,0,1] neg_lo:[0,1,0] neg_hi:[0,1,0]
	v_pk_fma_f32 v[4:5], v[46:47], v[160:161], v[150:151] op_sel:[0,1,0] op_sel_hi:[1,1,1] neg_lo:[0,1,0] neg_hi:[0,1,0]
	v_pk_add_f32 v[128:129], v[162:163], v[144:145]
	v_pk_fma_f32 v[14:15], v[48:49], v[160:161], v[140:141] op_sel_hi:[1,0,1] neg_lo:[0,1,0] neg_hi:[0,1,0]
	v_pk_fma_f32 v[6:7], v[48:49], v[160:161], v[152:153] op_sel:[0,1,0] op_sel_hi:[1,1,1] neg_lo:[0,1,0] neg_hi:[0,1,0]
	v_pk_fma_f32 v[16:17], v[50:51], v[160:161], v[142:143] op_sel_hi:[1,0,1] neg_lo:[0,1,0] neg_hi:[0,1,0]
	v_pk_fma_f32 v[8:9], v[50:51], v[160:161], v[154:155] op_sel:[0,1,0] op_sel_hi:[1,1,1] neg_lo:[0,1,0] neg_hi:[0,1,0]
	ds_write2_b32 v156, v128, v129 offset0:0 offset1:8
	ds_read_b128 v[28:31], v130 offset:9312
	ds_read_b128 v[32:35], v130 offset:9328
	ds_read_b128 v[36:39], v130 offset:9568
	ds_read_b128 v[40:43], v130 offset:9584
	ds_read_b128 v[44:47], v130 offset:9824
	ds_read_b128 v[48:51], v130 offset:9840
	ds_read_b128 v[52:55], v130 offset:10080
	ds_read_b128 v[56:59], v130 offset:10096
	ds_read_b128 v[60:63], v130 offset:10336
	ds_read_b128 v[64:67], v130 offset:10352
	ds_read_b32 v68, v132 offset:9312
	ds_read_b32 v69, v132 offset:9344
	ds_read_b64 v[70:71], v133 offset:10848
	s_waitcnt lgkmcnt(13)
; #define LAS __attribute__((address_space(3)))
; template <int R>
; __device__ __forceinline__ void rw_task(const Params& p, LAS unsigned char* shm, const int tid, const int s, const int d, const int h, const int half) {
;     ...
;                     const float v0 = sb[320 + row0], v1 = R == 2 ? sb[320 + row1] : 0.f; const f32x2 sc = *(const LAS f32x2*)(sb + 384); const float br = sc[0], kr = sc[1];
;                     if constexpr (R == 2) {
;                     f32x2 pa0 = s0[0] * kk[0], px0 = s0[0] * wr[0], pa1 = s1[0] * kk[0], px1 = s1[0] * wr[0];
; #pragma unroll
;                     for (int e = 1; e < 4; ++e) { pa0 += s0[e] * kk[e]; px0 += s0[e] * wr[e]; pa1 += s1[e] * kk[e]; px1 += s1[e] * wr[e]; }
;                     const float sa0 = red8(pa0[0] + pa0[1]), x0 = red8(px0[0] + px0[1]), sa1 = red8(pa1[0] + pa1[1]), x1 = red8(px1[0] + px1[1]);
;                     const float o0 = x0 - sa0 * br + v0 * kr, o1 = x1 - sa1 * br + v1 * kr;
;                     const f32x2 nsa0 = (f32x2){-sa0, -sa0}, nsa1 = (f32x2){-sa1, -sa1}, vv0 = (f32x2){v0, v0}, vv1 = (f32x2){v1, v1};
; #pragma unroll
;                     for (int e = 0; e < 4; ++e) { s0[e] = s0[e] * ww[e] + nsa0 * bb[e] + vv0 * kc[e]; s1[e] = s1[e] * ww[e] + nsa1 * bb[e] + vv1 * kc[e]; }
;                     ow0[(st * 64) & omask] = o0; ow1[(st * 64) & omask] = o1;
	v_pk_mul_f32 v[120:121], v[10:11], v[82:83]
	v_pk_mul_f32 v[124:125], v[2:3], v[82:83]
	v_pk_mul_f32 v[122:123], v[10:11], v[108:109]
	v_pk_mul_f32 v[126:127], v[2:3], v[108:109]
	v_pk_fma_f32 v[120:121], v[12:13], v[84:85], v[120:121]
	v_pk_fma_f32 v[124:125], v[4:5], v[84:85], v[124:125]
	v_pk_fma_f32 v[122:123], v[12:13], v[110:111], v[122:123]
	v_pk_fma_f32 v[126:127], v[4:5], v[110:111], v[126:127]
	v_pk_fma_f32 v[120:121], v[14:15], v[86:87], v[120:121]
	v_pk_fma_f32 v[124:125], v[6:7], v[86:87], v[124:125]
	v_pk_fma_f32 v[122:123], v[14:15], v[112:113], v[122:123]
	v_pk_fma_f32 v[126:127], v[6:7], v[112:113], v[126:127]
	v_pk_fma_f32 v[120:121], v[16:17], v[88:89], v[120:121]
	v_pk_fma_f32 v[124:125], v[8:9], v[88:89], v[124:125]
	v_pk_fma_f32 v[122:123], v[16:17], v[114:115], v[122:123]
	v_pk_fma_f32 v[126:127], v[8:9], v[114:115], v[126:127]
	v_pk_mul_f32 v[136:137], v[10:11], v[74:75]
	v_pk_mul_f32 v[148:149], v[2:3], v[74:75]
	v_add_f32_e32 v160, v120, v121
	v_add_f32_e32 v161, v124, v125
	v_add_f32_e32 v162, v122, v123
	v_add_f32_e32 v163, v126, v127
	v_pk_mul_f32 v[138:139], v[12:13], v[76:77]
	v_pk_mul_f32 v[150:151], v[4:5], v[76:77]
	v_add_f32_dpp v160, v160, v160 quad_perm:[1,0,3,2] row_mask:0xf bank_mask:0xf bound_ctrl:1
	v_add_f32_dpp v161, v161, v161 quad_perm:[1,0,3,2] row_mask:0xf bank_mask:0xf bound_ctrl:1
	v_pk_mul_f32 v[140:141], v[14:15], v[78:79]
	v_pk_mul_f32 v[152:153], v[6:7], v[78:79]
	v_add_f32_dpp v162, v162, v162 quad_perm:[1,0,3,2] row_mask:0xf bank_mask:0xf bound_ctrl:1
	v_add_f32_dpp v163, v163, v163 quad_perm:[1,0,3,2] row_mask:0xf bank_mask:0xf bound_ctrl:1
	v_pk_mul_f32 v[142:143], v[16:17], v[80:81]
	v_pk_mul_f32 v[154:155], v[8:9], v[80:81]
	v_add_f32_dpp v160, v160, v160 quad_perm:[2,3,0,1] row_mask:0xf bank_mask:0xf bound_ctrl:1
	v_add_f32_dpp v161, v161, v161 quad_perm:[2,3,0,1] row_mask:0xf bank_mask:0xf bound_ctrl:1
	v_pk_fma_f32 v[136:137], v[100:101], v[116:117], v[136:137] op_sel_hi:[1,0,1]
	v_pk_fma_f32 v[148:149], v[100:101], v[116:117], v[148:149] op_sel:[0,1,0] op_sel_hi:[1,1,1]
	v_add_f32_dpp v162, v162, v162 quad_perm:[2,3,0,1] row_mask:0xf bank_mask:0xf bound_ctrl:1
	v_add_f32_dpp v163, v163, v163 quad_perm:[2,3,0,1] row_mask:0xf bank_mask:0xf bound_ctrl:1
	v_pk_fma_f32 v[138:139], v[102:103], v[116:117], v[138:139] op_sel_hi:[1,0,1]
	v_pk_fma_f32 v[150:151], v[102:103], v[116:117], v[150:151] op_sel:[0,1,0] op_sel_hi:[1,1,1]
	v_add_f32_dpp v160, v160, v160 row_half_mirror row_mask:0xf bank_mask:0xf bound_ctrl:1
	v_add_f32_dpp v161, v161, v161 row_half_mirror row_mask:0xf bank_mask:0xf bound_ctrl:1
	v_pk_fma_f32 v[140:141], v[104:105], v[116:117], v[140:141] op_sel_hi:[1,0,1]
	v_pk_fma_f32 v[152:153], v[104:105], v[116:117], v[152:153] op_sel:[0,1,0] op_sel_hi:[1,1,1]
	v_add_f32_dpp v162, v162, v162 row_half_mirror row_mask:0xf bank_mask:0xf bound_ctrl:1
	v_add_f32_dpp v163, v163, v163 row_half_mirror row_mask:0xf bank_mask:0xf bound_ctrl:1
	v_pk_fma_f32 v[142:143], v[106:107], v[116:117], v[142:143] op_sel_hi:[1,0,1]
	v_pk_fma_f32 v[154:155], v[106:107], v[116:117], v[154:155] op_sel:[0,1,0] op_sel_hi:[1,1,1]
	v_pk_mul_f32 v[144:145], v[116:117], v[118:119] op_sel:[0,1] op_sel_hi:[1,1]
	v_pk_fma_f32 v[10:11], v[92:93], v[160:161], v[136:137] op_sel_hi:[1,0,1] neg_lo:[0,1,0] neg_hi:[0,1,0]
	v_pk_fma_f32 v[2:3], v[92:93], v[160:161], v[148:149] op_sel:[0,1,0] op_sel_hi:[1,1,1] neg_lo:[0,1,0] neg_hi:[0,1,0]
	v_pk_fma_f32 v[144:145], v[160:161], v[118:119], v[144:145] op_sel_hi:[1,0,1] neg_lo:[1,0,0] neg_hi:[1,0,0]
	v_pk_fma_f32 v[12:13], v[94:95], v[160:161], v[138:139] op_sel_hi:[1,0,1] neg_lo:[0,1,0] neg_hi:[0,1,0]
	v_pk_fma_f32 v[4:5], v[94:95], v[160:161], v[150:151] op_sel:[0,1,0] op_sel_hi:[1,1,1] neg_lo:[0,1,0] neg_hi:[0,1,0]
	v_pk_add_f32 v[128:129], v[162:163], v[144:145]
	v_pk_fma_f32 v[14:15], v[96:97], v[160:161], v[140:141] op_sel_hi:[1,0,1] neg_lo:[0,1,0] neg_hi:[0,1,0]
	v_pk_fma_f32 v[6:7], v[96:97], v[160:161], v[152:153] op_sel:[0,1,0] op_sel_hi:[1,1,1] neg_lo:[0,1,0] neg_hi:[0,1,0]
	v_pk_fma_f32 v[16:17], v[98:99], v[160:161], v[142:143] op_sel_hi:[1,0,1] neg_lo:[0,1,0] neg_hi:[0,1,0]
	v_pk_fma_f32 v[8:9], v[98:99], v[160:161], v[154:155] op_sel:[0,1,0] op_sel_hi:[1,1,1] neg_lo:[0,1,0] neg_hi:[0,1,0]
	ds_write2_b32 v156, v128, v129 offset0:64 offset1:72
	ds_read_b128 v[74:77], v130 offset:10864
	ds_read_b128 v[78:81], v130 offset:10880
	ds_read_b128 v[82:85], v130 offset:11120
	ds_read_b128 v[86:89], v130 offset:11136
	ds_read_b128 v[92:95], v130 offset:11376
	ds_read_b128 v[96:99], v130 offset:11392
	ds_read_b128 v[100:103], v130 offset:11632
	ds_read_b128 v[104:107], v130 offset:11648
	ds_read_b128 v[108:111], v130 offset:11888
	ds_read_b128 v[112:115], v130 offset:11904
	ds_read_b32 v116, v132 offset:10864
	ds_read_b32 v117, v132 offset:10896
	ds_read_b64 v[118:119], v133 offset:12400
	s_waitcnt lgkmcnt(13)
; #define LAS __attribute__((address_space(3)))
; template <int R>
; __device__ __forceinline__ void rw_task(const Params& p, LAS unsigned char* shm, const int tid, const int s, const int d, const int h, const int half) {
;     ...
;                     const float v0 = sb[320 + row0], v1 = R == 2 ? sb[320 + row1] : 0.f; const f32x2 sc = *(const LAS f32x2*)(sb + 384); const float br = sc[0], kr = sc[1];
;                     if constexpr (R == 2) {
;                     f32x2 pa0 = s0[0] * kk[0], px0 = s0[0] * wr[0], pa1 = s1[0] * kk[0], px1 = s1[0] * wr[0];
; #pragma unroll
;                     for (int e = 1; e < 4; ++e) { pa0 += s0[e] * kk[e]; px0 += s0[e] * wr[e]; pa1 += s1[e] * kk[e]; px1 += s1[e] * wr[e]; }
;                     const float sa0 = red8(pa0[0] + pa0[1]), x0 = red8(px0[0] + px0[1]), sa1 = red8(pa1[0] + pa1[1]), x1 = red8(px1[0] + px1[1]);
;                     const float o0 = x0 - sa0 * br + v0 * kr, o1 = x1 - sa1 * br + v1 * kr;
;                     const f32x2 nsa0 = (f32x2){-sa0, -sa0}, nsa1 = (f32x2){-sa1, -sa1}, vv0 = (f32x2){v0, v0}, vv1 = (f32x2){v1, v1};
; #pragma unroll
;                     for (int e = 0; e < 4; ++e) { s0[e] = s0[e] * ww[e] + nsa0 * bb[e] + vv0 * kc[e]; s1[e] = s1[e] * ww[e] + nsa1 * bb[e] + vv1 * kc[e]; }
;                     ow0[(st * 64) & omask] = o0; ow1[(st * 64) & omask] = o1;
	v_pk_mul_f32 v[120:121], v[10:11], v[36:37]
	v_pk_mul_f32 v[124:125], v[2:3], v[36:37]
	v_pk_mul_f32 v[122:123], v[10:11], v[60:61]
	v_pk_mul_f32 v[126:127], v[2:3], v[60:61]
	v_pk_fma_f32 v[120:121], v[12:13], v[38:39], v[120:121]
	v_pk_fma_f32 v[124:125], v[4:5], v[38:39], v[124:125]
	v_pk_fma_f32 v[122:123], v[12:13], v[62:63], v[122:123]
	v_pk_fma_f32 v[126:127], v[4:5], v[62:63], v[126:127]
	v_pk_fma_f32 v[120:121], v[14:15], v[40:41], v[120:121]
	v_pk_fma_f32 v[124:125], v[6:7], v[40:41], v[124:125]
	v_pk_fma_f32 v[122:123], v[14:15], v[64:65], v[122:123]
	v_pk_fma_f32 v[126:127], v[6:7], v[64:65], v[126:127]
	v_pk_fma_f32 v[120:121], v[16:17], v[42:43], v[120:121]
	v_pk_fma_f32 v[124:125], v[8:9], v[42:43], v[124:125]
	v_pk_fma_f32 v[122:123], v[16:17], v[66:67], v[122:123]
	v_pk_fma_f32 v[126:127], v[8:9], v[66:67], v[126:127]
	v_pk_mul_f32 v[136:137], v[10:11], v[28:29]
	v_pk_mul_f32 v[148:149], v[2:3], v[28:29]
	v_add_f32_e32 v160, v120, v121
	v_add_f32_e32 v161, v124, v125
	v_add_f32_e32 v162, v122, v123
	v_add_f32_e32 v163, v126, v127
	v_pk_mul_f32 v[138:139], v[12:13], v[30:31]
	v_pk_mul_f32 v[150:151], v[4:5], v[30:31]
	v_add_f32_dpp v160, v160, v160 quad_perm:[1,0,3,2] row_mask:0xf bank_mask:0xf bound_ctrl:1
	v_add_f32_dpp v161, v161, v161 quad_perm:[1,0,3,2] row_mask:0xf bank_mask:0xf bound_ctrl:1
	v_pk_mul_f32 v[140:141], v[14:15], v[32:33]
	v_pk_mul_f32 v[152:153], v[6:7], v[32:33]
	v_add_f32_dpp v162, v162, v162 quad_perm:[1,0,3,2] row_mask:0xf bank_mask:0xf bound_ctrl:1
	v_add_f32_dpp v163, v163, v163 quad_perm:[1,0,3,2] row_mask:0xf bank_mask:0xf bound_ctrl:1
	v_pk_mul_f32 v[142:143], v[16:17], v[34:35]
	v_pk_mul_f32 v[154:155], v[8:9], v[34:35]
	v_add_f32_dpp v160, v160, v160 quad_perm:[2,3,0,1] row_mask:0xf bank_mask:0xf bound_ctrl:1
	v_add_f32_dpp v161, v161, v161 quad_perm:[2,3,0,1] row_mask:0xf bank_mask:0xf bound_ctrl:1
	v_pk_fma_f32 v[136:137], v[52:53], v[68:69], v[136:137] op_sel_hi:[1,0,1]
	v_pk_fma_f32 v[148:149], v[52:53], v[68:69], v[148:149] op_sel:[0,1,0] op_sel_hi:[1,1,1]
	v_add_f32_dpp v162, v162, v162 quad_perm:[2,3,0,1] row_mask:0xf bank_mask:0xf bound_ctrl:1
	v_add_f32_dpp v163, v163, v163 quad_perm:[2,3,0,1] row_mask:0xf bank_mask:0xf bound_ctrl:1
	v_pk_fma_f32 v[138:139], v[54:55], v[68:69], v[138:139] op_sel_hi:[1,0,1]
	v_pk_fma_f32 v[150:151], v[54:55], v[68:69], v[150:151] op_sel:[0,1,0] op_sel_hi:[1,1,1]
	v_add_f32_dpp v160, v160, v160 row_half_mirror row_mask:0xf bank_mask:0xf bound_ctrl:1
	v_add_f32_dpp v161, v161, v161 row_half_mirror row_mask:0xf bank_mask:0xf bound_ctrl:1
	v_pk_fma_f32 v[140:141], v[56:57], v[68:69], v[140:141] op_sel_hi:[1,0,1]
	v_pk_fma_f32 v[152:153], v[56:57], v[68:69], v[152:153] op_sel:[0,1,0] op_sel_hi:[1,1,1]
	v_add_f32_dpp v162, v162, v162 row_half_mirror row_mask:0xf bank_mask:0xf bound_ctrl:1
	v_add_f32_dpp v163, v163, v163 row_half_mirror row_mask:0xf bank_mask:0xf bound_ctrl:1
	v_pk_fma_f32 v[142:143], v[58:59], v[68:69], v[142:143] op_sel_hi:[1,0,1]
	v_pk_fma_f32 v[154:155], v[58:59], v[68:69], v[154:155] op_sel:[0,1,0] op_sel_hi:[1,1,1]
	v_pk_mul_f32 v[144:145], v[68:69], v[70:71] op_sel:[0,1] op_sel_hi:[1,1]
	v_pk_fma_f32 v[10:11], v[44:45], v[160:161], v[136:137] op_sel_hi:[1,0,1] neg_lo:[0,1,0] neg_hi:[0,1,0]
	v_pk_fma_f32 v[2:3], v[44:45], v[160:161], v[148:149] op_sel:[0,1,0] op_sel_hi:[1,1,1] neg_lo:[0,1,0] neg_hi:[0,1,0]
	v_pk_fma_f32 v[144:145], v[160:161], v[70:71], v[144:145] op_sel_hi:[1,0,1] neg_lo:[1,0,0] neg_hi:[1,0,0]
	v_pk_fma_f32 v[12:13], v[46:47], v[160:161], v[138:139] op_sel_hi:[1,0,1] neg_lo:[0,1,0] neg_hi:[0,1,0]
	v_pk_fma_f32 v[4:5], v[46:47], v[160:161], v[150:151] op_sel:[0,1,0] op_sel_hi:[1,1,1] neg_lo:[0,1,0] neg_hi:[0,1,0]
	v_pk_add_f32 v[128:129], v[162:163], v[144:145]
	v_pk_fma_f32 v[14:15], v[48:49], v[160:161], v[140:141] op_sel_hi:[1,0,1] neg_lo:[0,1,0] neg_hi:[0,1,0]
	v_pk_fma_f32 v[6:7], v[48:49], v[160:161], v[152:153] op_sel:[0,1,0] op_sel_hi:[1,1,1] neg_lo:[0,1,0] neg_hi:[0,1,0]
	v_pk_fma_f32 v[16:17], v[50:51], v[160:161], v[142:143] op_sel_hi:[1,0,1] neg_lo:[0,1,0] neg_hi:[0,1,0]
	v_pk_fma_f32 v[8:9], v[50:51], v[160:161], v[154:155] op_sel:[0,1,0] op_sel_hi:[1,1,1] neg_lo:[0,1,0] neg_hi:[0,1,0]
	ds_write2_b32 v156, v128, v129 offset0:128 offset1:136
	ds_read_b128 v[28:31], v130 offset:12416
	ds_read_b128 v[32:35], v130 offset:12432
	ds_read_b128 v[36:39], v130 offset:12672
	ds_read_b128 v[40:43], v130 offset:12688
	ds_read_b128 v[44:47], v130 offset:12928
	ds_read_b128 v[48:51], v130 offset:12944
	ds_read_b128 v[52:55], v130 offset:13184
	ds_read_b128 v[56:59], v130 offset:13200
	ds_read_b128 v[60:63], v130 offset:13440
	ds_read_b128 v[64:67], v130 offset:13456
	ds_read_b32 v68, v132 offset:12416
	ds_read_b32 v69, v132 offset:12448
	ds_read_b64 v[70:71], v133 offset:13952
	s_waitcnt lgkmcnt(13)
; #define LAS __attribute__((address_space(3)))
; template <int R>
; __device__ __forceinline__ void rw_task(const Params& p, LAS unsigned char* shm, const int tid, const int s, const int d, const int h, const int half) {
;     ...
;                 for (int st = 0; st < TT; ++st) {
;                     const LAS float* sb = ib + st * RW_STRIDE;
;                     f32x2 ww[4], kk[4], bb[4], kc[4], wr[4];
;                     { const f32x4 a = *(const LAS f32x4*)(sb + 8 * j), b = *(const LAS f32x4*)(sb + 8 * j + 4); ww[0] = (f32x2){a[0], a[1]}; ww[1] = (f32x2){a[2], a[3]}; ww[2] = (f32x2){b[0], b[1]}; ww[3] = (f32x2){b[2], b[3]}; }
;                     { const f32x4 a = *(const LAS f32x4*)(sb + 64 + 8 * j), b = *(const LAS f32x4*)(sb + 64 + 8 * j + 4); kk[0] = (f32x2){a[0], a[1]}; kk[1] = (f32x2){a[2], a[3]}; kk[2] = (f32x2){b[0], b[1]}; kk[3] = (f32x2){b[2], b[3]}; }
;                     { const f32x4 a = *(const LAS f32x4*)(sb + 128 + 8 * j), b = *(const LAS f32x4*)(sb + 128 + 8 * j + 4); bb[0] = (f32x2){a[0], a[1]}; bb[1] = (f32x2){a[2], a[3]}; bb[2] = (f32x2){b[0], b[1]}; bb[3] = (f32x2){b[2], b[3]}; }
;                     { const f32x4 a = *(const LAS f32x4*)(sb + 192 + 8 * j), b = *(const LAS f32x4*)(sb + 192 + 8 * j + 4); kc[0] = (f32x2){a[0], a[1]}; kc[1] = (f32x2){a[2], a[3]}; kc[2] = (f32x2){b[0], b[1]}; kc[3] = (f32x2){b[2], b[3]}; }
;                     { const f32x4 a = *(const LAS f32x4*)(sb + 256 + 8 * j), b = *(const LAS f32x4*)(sb + 256 + 8 * j + 4); wr[0] = (f32x2){a[0], a[1]}; wr[1] = (f32x2){a[2], a[3]}; wr[2] = (f32x2){b[0], b[1]}; wr[3] = (f32x2){b[2], b[3]}; }
;                     const float v0 = sb[320 + row0], v1 = R == 2 ? sb[320 + row1] : 0.f; const f32x2 sc = *(const LAS f32x2*)(sb + 384); const float br = sc[0], kr = sc[1];
;                     if constexpr (R == 2) {
;                     f32x2 pa0 = s0[0] * kk[0], px0 = s0[0] * wr[0], pa1 = s1[0] * kk[0], px1 = s1[0] * wr[0];
; #pragma unroll
;                     for (int e = 1; e < 4; ++e) { pa0 += s0[e] * kk[e]; px0 += s0[e] * wr[e]; pa1 += s1[e] * kk[e]; px1 += s1[e] * wr[e]; }
;                     const float sa0 = red8(pa0[0] + pa0[1]), x0 = red8(px0[0] + px0[1]), sa1 = red8(pa1[0] + pa1[1]), x1 = red8(px1[0] + px1[1]);
;                     const float o0 = x0 - sa0 * br + v0 * kr, o1 = x1 - sa1 * br + v1 * kr;
	v_pk_mul_f32 v[120:121], v[10:11], v[82:83]
	v_pk_mul_f32 v[124:125], v[2:3], v[82:83]
	v_pk_mul_f32 v[122:123], v[10:11], v[108:109]
	v_pk_mul_f32 v[126:127], v[2:3], v[108:109]
	v_pk_fma_f32 v[120:121], v[12:13], v[84:85], v[120:121]
	v_pk_fma_f32 v[124:125], v[4:5], v[84:85], v[124:125]
	v_pk_fma_f32 v[122:123], v[12:13], v[110:111], v[122:123]
	v_pk_fma_f32 v[126:127], v[4:5], v[110:111], v[126:127]
	v_pk_fma_f32 v[120:121], v[14:15], v[86:87], v[120:121]
	v_pk_fma_f32 v[124:125], v[6:7], v[86:87], v[124:125]
	v_pk_fma_f32 v[122:123], v[14:15], v[112:113], v[122:123]
	v_pk_fma_f32 v[126:127], v[6:7], v[112:113], v[126:127]
	v_pk_fma_f32 v[120:121], v[16:17], v[88:89], v[120:121]
	v_pk_fma_f32 v[124:125], v[8:9], v[88:89], v[124:125]
	v_pk_fma_f32 v[122:123], v[16:17], v[114:115], v[122:123]
	v_pk_fma_f32 v[126:127], v[8:9], v[114:115], v[126:127]
	v_pk_mul_f32 v[136:137], v[10:11], v[74:75]
	v_pk_mul_f32 v[148:149], v[2:3], v[74:75]
	v_add_f32_e32 v160, v120, v121
	v_add_f32_e32 v161, v124, v125
	v_add_f32_e32 v162, v122, v123
	v_add_f32_e32 v163, v126, v127
	v_pk_mul_f32 v[138:139], v[12:13], v[76:77]
	v_pk_mul_f32 v[150:151], v[4:5], v[76:77]
	v_add_f32_dpp v160, v160, v160 quad_perm:[1,0,3,2] row_mask:0xf bank_mask:0xf bound_ctrl:1
	v_add_f32_dpp v161, v161, v161 quad_perm:[1,0,3,2] row_mask:0xf bank_mask:0xf bound_ctrl:1
	v_pk_mul_f32 v[140:141], v[14:15], v[78:79]
	v_pk_mul_f32 v[152:153], v[6:7], v[78:79]
	v_add_f32_dpp v162, v162, v162 quad_perm:[1,0,3,2] row_mask:0xf bank_mask:0xf bound_ctrl:1
	v_add_f32_dpp v163, v163, v163 quad_perm:[1,0,3,2] row_mask:0xf bank_mask:0xf bound_ctrl:1
	v_pk_mul_f32 v[142:143], v[16:17], v[80:81]
	v_pk_mul_f32 v[154:155], v[8:9], v[80:81]
	v_add_f32_dpp v160, v160, v160 quad_perm:[2,3,0,1] row_mask:0xf bank_mask:0xf bound_ctrl:1
	v_add_f32_dpp v161, v161, v161 quad_perm:[2,3,0,1] row_mask:0xf bank_mask:0xf bound_ctrl:1
	v_pk_fma_f32 v[136:137], v[100:101], v[116:117], v[136:137] op_sel_hi:[1,0,1]
	v_pk_fma_f32 v[148:149], v[100:101], v[116:117], v[148:149] op_sel:[0,1,0] op_sel_hi:[1,1,1]
	v_add_f32_dpp v162, v162, v162 quad_perm:[2,3,0,1] row_mask:0xf bank_mask:0xf bound_ctrl:1
	v_add_f32_dpp v163, v163, v163 quad_perm:[2,3,0,1] row_mask:0xf bank_mask:0xf bound_ctrl:1
	v_pk_fma_f32 v[138:139], v[102:103], v[116:117], v[138:139] op_sel_hi:[1,0,1]
	v_pk_fma_f32 v[150:151], v[102:103], v[116:117], v[150:151] op_sel:[0,1,0] op_sel_hi:[1,1,1]
	v_add_f32_dpp v160, v160, v160 row_half_mirror row_mask:0xf bank_mask:0xf bound_ctrl:1
	v_add_f32_dpp v161, v161, v161 row_half_mirror row_mask:0xf bank_mask:0xf bound_ctrl:1
	v_pk_fma_f32 v[140:141], v[104:105], v[116:117], v[140:141] op_sel_hi:[1,0,1]
	v_pk_fma_f32 v[152:153], v[104:105], v[116:117], v[152:153] op_sel:[0,1,0] op_sel_hi:[1,1,1]
	v_add_f32_dpp v162, v162, v162 row_half_mirror row_mask:0xf bank_mask:0xf bound_ctrl:1
	v_add_f32_dpp v163, v163, v163 row_half_mirror row_mask:0xf bank_mask:0xf bound_ctrl:1
	v_pk_fma_f32 v[142:143], v[106:107], v[116:117], v[142:143] op_sel_hi:[1,0,1]
	v_pk_fma_f32 v[154:155], v[106:107], v[116:117], v[154:155] op_sel:[0,1,0] op_sel_hi:[1,1,1]
	v_pk_mul_f32 v[144:145], v[116:117], v[118:119] op_sel:[0,1] op_sel_hi:[1,1]
	v_pk_fma_f32 v[10:11], v[92:93], v[160:161], v[136:137] op_sel_hi:[1,0,1] neg_lo:[0,1,0] neg_hi:[0,1,0]
	v_pk_fma_f32 v[2:3], v[92:93], v[160:161], v[148:149] op_sel:[0,1,0] op_sel_hi:[1,1,1] neg_lo:[0,1,0] neg_hi:[0,1,0]
	v_pk_fma_f32 v[144:145], v[160:161], v[118:119], v[144:145] op_sel_hi:[1,0,1] neg_lo:[1,0,0] neg_hi:[1,0,0]
	v_pk_fma_f32 v[12:13], v[94:95], v[160:161], v[138:139] op_sel_hi:[1,0,1] neg_lo:[0,1,0] neg_hi:[0,1,0]
	v_pk_fma_f32 v[4:5], v[94:95], v[160:161], v[150:151] op_sel:[0,1,0] op_sel_hi:[1,1,1] neg_lo:[0,1,0] neg_hi:[0,1,0]
	v_pk_add_f32 v[128:129], v[162:163], v[144:145]
	v_pk_fma_f32 v[14:15], v[96:97], v[160:161], v[140:141] op_sel_hi:[1,0,1] neg_lo:[0,1,0] neg_hi:[0,1,0]
	v_pk_fma_f32 v[6:7], v[96:97], v[160:161], v[152:153] op_sel:[0,1,0] op_sel_hi:[1,1,1] neg_lo:[0,1,0] neg_hi:[0,1,0]
	v_pk_fma_f32 v[16:17], v[98:99], v[160:161], v[142:143] op_sel_hi:[1,0,1] neg_lo:[0,1,0] neg_hi:[0,1,0]
	v_pk_fma_f32 v[8:9], v[98:99], v[160:161], v[154:155] op_sel:[0,1,0] op_sel_hi:[1,1,1] neg_lo:[0,1,0] neg_hi:[0,1,0]
	ds_write2_b32 v156, v128, v129 offset0:192 offset1:200
	v_add_u32_e32 v156, 0x400, v156
	v_add_u32_e32 v130, 0x3080, v130
	v_add_u32_e32 v132, 0x3080, v132
	v_add_u32_e32 v133, 0x3080, v133
	s_add_i32 s6, s6, 1
	s_cmp_eq_u32 s6, 4
	s_cbranch_scc0 .Lrw2_step
	s_add_i32 s4, s4, 1
	s_xor_b64 s[0:1], s[0:1], -1
	s_cmpk_eq_i32 s4, 0x80
	s_waitcnt lgkmcnt(0)
	s_barrier
	s_cbranch_scc0 .LBB0_205
